# adds P3 Wo epilogue: X1B image-layout stores transposed through the LDS scratch (1 KiB contiguous per store instruction), deferred commits
# baseline (speedup 1.0000x reference)
; __host__ __device__ __forceinline__ size_t img_off(int row, int col, int nkt) { return ((size_t)((row >> 7) * nkt + (col >> 6)) << 14) + (size_t)lds_byte(row & 127, col & 63); }
;     __device__ __forceinline__ void operator()(const f32x4 (&acc)[2][2][4][2], const Unit& u, int wr, int wc, int fr, int fq) const {
;     ...
;                     *(u32x4*)((char*)x1b + img_off(row, col0 + bj * HALF, 16)) = w; }
; __global__ void __launch_bounds__(NWAVES * 64, 2) hymba_fwd(Args args) {
;     ...
;     if (IN(3)) {
;         pg8::Gemm g{(const bf16*)(ws + WS_MIX), (const bf16*)(ws + WS_WO), MP, DM, DM};
;         pg8::EpiWo E{args.in[4], ws};
;         pg8::StaticOrder S; S.init(MP, DM, F.G, (int)blockIdx.x);
;         pg8::gemm_phase<pg8::EpiWo, pg8::StaticOrder, PG8_ALIGN, PG8_SP2>(F.lds + RING_OFF, g, S, E);
.LBB0_861:
	s_cmp_lt_i32 s92, 4
	s_cselect_b64 s[0:1], -1, 0
	s_cmp_gt_i32 s93, 3
	s_cselect_b64 s[2:3], -1, 0
	s_and_b64 s[0:1], s[0:1], s[2:3]
	s_andn2_b64 vcc, exec, s[0:1]
	s_cbranch_vccnz .LBB0_963
	v_and_b32_e32 v224, 63, v0
	v_lshrrev_b32_e32 v225, 6, v0
	v_lshlrev_b32_e32 v225, 11, v225
	v_add_u32_e32 v225, 0x24000, v225
	v_lshlrev_b32_e32 v218, 4, v224
	v_and_b32_e32 v226, 15, v224
	v_lshrrev_b32_e32 v227, 4, v224
	v_and_b32_e32 v228, 3, v226
	v_xor_b32_e32 v228, v227, v228
	v_lshlrev_b32_e32 v228, 4, v228
	v_lshl_add_u32 v228, v226, 6, v228
	v_add_u32_e32 v216, v225, v228
	v_lshrrev_b32_e32 v226, 2, v224
	v_lshrrev_b32_e32 v227, 5, v224
	v_and_b32_e32 v228, 3, v224
	v_lshlrev_b32_e32 v227, 1, v227
	v_xor_b32_e32 v228, v228, v227
	v_and_b32_e32 v227, 3, v226
	v_xor_b32_e32 v228, v228, v227
	v_lshlrev_b32_e32 v228, 4, v228
	v_lshl_add_u32 v228, v226, 6, v228
	v_add_u32_e32 v217, v225, v228
	s_cmpk_lt_i32 s96, 0x100
	s_cselect_b64 s[4:5], -1, 0
	s_cmpk_gt_i32 s96, 0xff
	v_readfirstlane_b32 s6, v0
	s_cbranch_scc1 .LBB0_868
	s_ashr_i32 s0, s96, 31
	s_lshr_b32 s0, s0, 29
	s_add_i32 s0, s96, s0
	s_and_b32 s1, s0, -8
	s_sub_i32 s1, s96, s1
	s_cmp_gt_i32 s1, -1
	s_cbranch_scc0 .LBB0_865
	s_lshl_b32 s7, s1, 5
	s_cbranch_execz .LBB0_866
	s_branch .LBB0_867

;     __device__ __forceinline__ void operator()(const f32x4 (&acc)[2][2][4][2], const Unit& u, int wr, int wc, int fr, int fq) const {
;         const int row0 = u.pm * BM + wr * 64 + fr; const int col0 = u.pn * BM + wc * 32 + 8 * fq;
;         const char* xn = (const char*)(ws + EW_XN); const float* rs = (const float*)ws + EC_RS; bf16_t* x1b = (bf16_t*)(ws + EW_X1B); float* ss = (float*)ws + EC_SS;
;         f32x4 gi[2][2];
; #pragma unroll
;         for (int bj = 0; bj < 2; ++bj)
; #pragma unroll
;             for (int n = 0; n < 2; ++n) { const f32x4 g = *(const f32x4*)(ga + col0 + bj * HALF + 4 * n); gi[bj][n] = (f32x4){1.0f / g[0], 1.0f / g[1], 1.0f / g[2], 1.0f / g[3]}; }
.LBB0_884:
	s_lshl_b32 s12, s12, 8
	s_or_b32 s12, s12, s72
	v_or_b32_e32 v154, s12, v157
	v_readlane_b32 s80, v251, 14
	v_ashrrev_i32_e32 v155, 31, v154
	v_readlane_b32 s88, v251, 22
	v_readlane_b32 s89, v251, 23
	s_lshl_b32 s13, s60, 8
	s_add_i32 s13, s13, s71
	v_lshl_add_u64 v[134:135], v[154:155], 2, s[88:89]
	global_load_dwordx4 v[130:133], v[134:135], off offset:16
	global_load_dwordx4 v[144:147], v[134:135], off
	s_bfe_u32 s53, s72, 0x10005
	s_ashr_i32 s64, s12, 6
	v_readlane_b32 s81, v251, 15
	v_readlane_b32 s82, v251, 16
	v_readlane_b32 s83, v251, 17
	v_readlane_b32 s84, v251, 18
	v_readlane_b32 s85, v251, 19
	v_readlane_b32 s86, v251, 20
	v_readlane_b32 s87, v251, 21
	v_readlane_b32 s90, v251, 24
	v_readlane_b32 s91, v251, 25
	v_readlane_b32 s92, v251, 26
	v_readlane_b32 s93, v251, 27
	v_readlane_b32 s94, v251, 28
	v_readlane_b32 s95, v251, 29
	s_waitcnt vmcnt(0)
	v_div_scale_f32 v136, s[48:49], v144, v144, 1.0
	v_rcp_f32_e32 v137, v136
	s_nop 0
	v_fma_f32 v148, -v136, v137, 1.0
	v_fmac_f32_e32 v137, v148, v137
	v_div_scale_f32 v148, vcc, 1.0, v144, 1.0
	v_mul_f32_e32 v149, v148, v137
	v_fma_f32 v150, -v136, v149, v148
	v_fmac_f32_e32 v149, v150, v137
	v_fma_f32 v136, -v136, v149, v148
	v_div_fmas_f32 v136, v136, v137, v149
	v_div_fixup_f32 v144, v136, v144, 1.0
	v_div_scale_f32 v136, s[48:49], v145, v145, 1.0
	v_rcp_f32_e32 v137, v136
	s_nop 0
	v_fma_f32 v148, -v136, v137, 1.0
	v_fmac_f32_e32 v137, v148, v137
	v_div_scale_f32 v148, vcc, 1.0, v145, 1.0
	v_mul_f32_e32 v149, v148, v137
	v_fma_f32 v150, -v136, v149, v148
	v_fmac_f32_e32 v149, v150, v137
	v_fma_f32 v136, -v136, v149, v148
	v_div_fmas_f32 v136, v136, v137, v149
	v_div_fixup_f32 v145, v136, v145, 1.0
	v_div_scale_f32 v136, s[48:49], v146, v146, 1.0
	v_rcp_f32_e32 v137, v136
	s_nop 0
	v_fma_f32 v148, -v136, v137, 1.0
	v_fmac_f32_e32 v137, v148, v137
	v_div_scale_f32 v148, vcc, 1.0, v146, 1.0
	v_mul_f32_e32 v149, v148, v137
	v_fma_f32 v150, -v136, v149, v148
	v_fmac_f32_e32 v149, v150, v137
	v_fma_f32 v136, -v136, v149, v148
	v_div_fmas_f32 v136, v136, v137, v149
	v_div_fixup_f32 v146, v136, v146, 1.0
	v_div_scale_f32 v136, s[48:49], v147, v147, 1.0
	v_rcp_f32_e32 v137, v136
	s_nop 0
	v_fma_f32 v148, -v136, v137, 1.0
	v_fmac_f32_e32 v137, v148, v137
	v_div_scale_f32 v148, vcc, 1.0, v147, 1.0
	v_mul_f32_e32 v149, v148, v137
	v_fma_f32 v150, -v136, v149, v148
	v_fmac_f32_e32 v149, v150, v137
	v_fma_f32 v136, -v136, v149, v148
	v_div_fmas_f32 v136, v136, v137, v149
	v_div_fixup_f32 v147, v136, v147, 1.0
	v_div_scale_f32 v136, s[48:49], v130, v130, 1.0
	v_rcp_f32_e32 v137, v136
	s_nop 0
	v_fma_f32 v148, -v136, v137, 1.0
	v_fmac_f32_e32 v137, v148, v137
	v_div_scale_f32 v148, vcc, 1.0, v130, 1.0
	v_mul_f32_e32 v149, v148, v137
	v_fma_f32 v150, -v136, v149, v148
	v_fmac_f32_e32 v149, v150, v137
	v_fma_f32 v136, -v136, v149, v148
	v_div_fmas_f32 v136, v136, v137, v149
	v_div_fixup_f32 v148, v136, v130, 1.0
	v_div_scale_f32 v130, s[48:49], v131, v131, 1.0
	v_rcp_f32_e32 v136, v130
	s_nop 0
	v_fma_f32 v137, -v130, v136, 1.0
	v_fmac_f32_e32 v136, v137, v136
	v_div_scale_f32 v137, vcc, 1.0, v131, 1.0
	v_mul_f32_e32 v149, v137, v136
	v_fma_f32 v150, -v130, v149, v137
	v_fmac_f32_e32 v149, v150, v136
	v_fma_f32 v130, -v130, v149, v137
	v_div_fmas_f32 v130, v130, v136, v149
	v_div_fixup_f32 v149, v130, v131, 1.0
	v_div_scale_f32 v130, s[48:49], v132, v132, 1.0
	v_rcp_f32_e32 v131, v130
	s_nop 0
	v_fma_f32 v136, -v130, v131, 1.0
	v_fmac_f32_e32 v131, v136, v131
	v_div_scale_f32 v136, vcc, 1.0, v132, 1.0
	v_mul_f32_e32 v137, v136, v131
	v_fma_f32 v150, -v130, v137, v136
	v_fmac_f32_e32 v137, v150, v131
	v_fma_f32 v130, -v130, v137, v136
	v_div_fmas_f32 v130, v130, v131, v137
	v_div_fixup_f32 v150, v130, v132, 1.0
	v_div_scale_f32 v130, s[48:49], v133, v133, 1.0
	v_rcp_f32_e32 v131, v130
	s_nop 0
	v_fma_f32 v132, -v130, v131, 1.0
	v_fmac_f32_e32 v131, v132, v131
	v_div_scale_f32 v132, vcc, 1.0, v133, 1.0
	v_mul_f32_e32 v136, v132, v131
	v_fma_f32 v137, -v130, v136, v132
	v_fmac_f32_e32 v136, v137, v131
	v_fma_f32 v130, -v130, v136, v132
	v_div_fmas_f32 v130, v130, v131, v136
	v_div_fixup_f32 v151, v130, v133, 1.0
	global_load_dwordx4 v[130:133], v[134:135], off offset:528
	s_nop 0
	global_load_dwordx4 v[134:137], v[134:135], off offset:512
	s_waitcnt vmcnt(0)
; __host__ __device__ __forceinline__ size_t img_off(int row, int col, int nkt) { return ((size_t)((row >> 7) * nkt + (col >> 6)) << 14) + (size_t)lds_byte(row & 127, col & 63); }
; __device__ __forceinline__ unsigned cvt_pk_bf16(float lo, float hi) { unsigned r; asm volatile("v_cvt_pk_bf16_f32 %0, %1, %2" : "=v"(r) : "v"(lo), "v"(hi)); return r; }
;     __device__ __forceinline__ void operator()(const f32x4 (&acc)[2][2][4][2], const Unit& u, int wr, int wc, int fr, int fq) const {
;     ...
;             for (int n = 0; n < 2; ++n) { const f32x4 g = *(const f32x4*)(ga + col0 + bj * HALF + 4 * n); gi[bj][n] = (f32x4){1.0f / g[0], 1.0f / g[1], 1.0f / g[2], 1.0f / g[3]}; }
; #pragma unroll
;         for (int ai = 0; ai < 2; ++ai)
; #pragma unroll
;             for (int m = 0; m < 4; ++m) { const int row = row0 + ai * HALF + m * 16; float s = 0.f; const float rinv = 1.0f / rs[row];
; #pragma unroll
;                 for (int bj = 0; bj < 2; ++bj) { const u32x4 xw = __builtin_nontemporal_load((const u32x4*)(xn + img_off(row, col0 + bj * HALF, 16)));
;                     const f32x4 x0 = (f32x4){__builtin_bit_cast(float, xw.x << 16), __builtin_bit_cast(float, xw.x & 0xffff0000u), __builtin_bit_cast(float, xw.y << 16), __builtin_bit_cast(float, xw.y & 0xffff0000u)} * rinv * gi[bj][0];
;                     const f32x4 x1 = (f32x4){__builtin_bit_cast(float, xw.z << 16), __builtin_bit_cast(float, xw.z & 0xffff0000u), __builtin_bit_cast(float, xw.w << 16), __builtin_bit_cast(float, xw.w & 0xffff0000u)} * rinv * gi[bj][1];
;                     const f32x4 v0 = acc[ai][bj][m][0] + x0, v1 = acc[ai][bj][m][1] + x1;
;                     s += (v0[0] * v0[0] + v0[1] * v0[1]) + (v0[2] * v0[2] + v0[3] * v0[3]) + (v1[0] * v1[0] + v1[1] * v1[1]) + (v1[2] * v1[2] + v1[3] * v1[3]);
;                     u32x4 w; w.x = cvt_pk_bf16(v0[0], v0[1]); w.y = cvt_pk_bf16(v0[2], v0[3]); w.z = cvt_pk_bf16(v1[0], v1[1]); w.w = cvt_pk_bf16(v1[2], v1[3]);
;                     *(u32x4*)((char*)x1b + img_off(row, col0 + bj * HALF, 16)) = w; }
	v_div_scale_f32 v152, s[48:49], v134, v134, 1.0
	v_rcp_f32_e32 v153, v152
	s_nop 0
	v_fma_f32 v155, -v152, v153, 1.0
	v_fmac_f32_e32 v153, v155, v153
	v_div_scale_f32 v155, vcc, 1.0, v134, 1.0
	v_mul_f32_e32 v156, v155, v153
	v_fma_f32 v158, -v152, v156, v155
	v_fmac_f32_e32 v156, v158, v153
	v_fma_f32 v152, -v152, v156, v155
	v_div_fmas_f32 v152, v152, v153, v156
	v_div_fixup_f32 v134, v152, v134, 1.0
	v_div_scale_f32 v152, s[48:49], v135, v135, 1.0
	v_rcp_f32_e32 v153, v152
	s_nop 0
	v_fma_f32 v155, -v152, v153, 1.0
	v_fmac_f32_e32 v153, v155, v153
	v_div_scale_f32 v155, vcc, 1.0, v135, 1.0
	v_mul_f32_e32 v156, v155, v153
	v_fma_f32 v158, -v152, v156, v155
	v_fmac_f32_e32 v156, v158, v153
	v_fma_f32 v152, -v152, v156, v155
	v_div_fmas_f32 v152, v152, v153, v156
	v_div_fixup_f32 v135, v152, v135, 1.0
	v_div_scale_f32 v152, s[48:49], v136, v136, 1.0
	v_rcp_f32_e32 v153, v152
	s_nop 0
	v_fma_f32 v155, -v152, v153, 1.0
	v_fmac_f32_e32 v153, v155, v153
	v_div_scale_f32 v155, vcc, 1.0, v136, 1.0
	v_mul_f32_e32 v156, v155, v153
	v_fma_f32 v158, -v152, v156, v155
	v_fmac_f32_e32 v156, v158, v153
	v_fma_f32 v152, -v152, v156, v155
	v_div_fmas_f32 v152, v152, v153, v156
	v_div_fixup_f32 v136, v152, v136, 1.0
	v_div_scale_f32 v152, s[48:49], v137, v137, 1.0
	v_rcp_f32_e32 v153, v152
	s_nop 0
	v_fma_f32 v155, -v152, v153, 1.0
	v_fmac_f32_e32 v153, v155, v153
	v_div_scale_f32 v155, vcc, 1.0, v137, 1.0
	v_mul_f32_e32 v156, v155, v153
	v_fma_f32 v158, -v152, v156, v155
	v_fmac_f32_e32 v156, v158, v153
	v_fma_f32 v152, -v152, v156, v155
	v_div_fmas_f32 v152, v152, v153, v156
	v_div_fixup_f32 v137, v152, v137, 1.0
	v_div_scale_f32 v152, s[48:49], v130, v130, 1.0
	v_rcp_f32_e32 v153, v152
	s_nop 0
	v_fma_f32 v155, -v152, v153, 1.0
	v_fmac_f32_e32 v153, v155, v153
	v_div_scale_f32 v155, vcc, 1.0, v130, 1.0
	v_mul_f32_e32 v156, v155, v153
	v_fma_f32 v158, -v152, v156, v155
	v_fmac_f32_e32 v156, v158, v153
	v_fma_f32 v152, -v152, v156, v155
	v_div_fmas_f32 v152, v152, v153, v156
	v_div_fixup_f32 v130, v152, v130, 1.0
	v_div_scale_f32 v152, s[48:49], v131, v131, 1.0
	v_rcp_f32_e32 v153, v152
	s_nop 0
	v_fma_f32 v155, -v152, v153, 1.0
	v_fmac_f32_e32 v153, v155, v153
	v_div_scale_f32 v155, vcc, 1.0, v131, 1.0
	v_mul_f32_e32 v156, v155, v153
	v_fma_f32 v158, -v152, v156, v155
	v_fmac_f32_e32 v156, v158, v153
	v_fma_f32 v152, -v152, v156, v155
	v_div_fmas_f32 v152, v152, v153, v156
	v_div_fixup_f32 v131, v152, v131, 1.0
	v_div_scale_f32 v152, s[48:49], v132, v132, 1.0
	v_rcp_f32_e32 v153, v152
	s_nop 0
	v_fma_f32 v155, -v152, v153, 1.0
	v_fmac_f32_e32 v153, v155, v153
	v_div_scale_f32 v155, vcc, 1.0, v132, 1.0
	v_mul_f32_e32 v156, v155, v153
	v_fma_f32 v158, -v152, v156, v155
	v_fmac_f32_e32 v156, v158, v153
	v_fma_f32 v152, -v152, v156, v155
	v_div_fmas_f32 v152, v152, v153, v156
	v_div_fixup_f32 v132, v152, v132, 1.0
	v_div_scale_f32 v152, s[48:49], v133, v133, 1.0
	v_rcp_f32_e32 v153, v152
	s_or_b32 s48, s64, 2
	v_fma_f32 v155, -v152, v153, 1.0
	v_fmac_f32_e32 v153, v155, v153
	v_div_scale_f32 v155, vcc, 1.0, v133, 1.0
	v_mul_f32_e32 v156, v155, v153
	v_fma_f32 v158, -v152, v156, v155
	v_fmac_f32_e32 v156, v158, v153
	v_fma_f32 v152, -v152, v156, v155
	v_div_fmas_f32 v152, v152, v153, v156
	v_div_fixup_f32 v133, v152, v133, 1.0
	v_or_b32_e32 v152, s13, v1
	v_lshlrev_b32_e32 v153, 1, v154
	v_and_b32_e32 v165, 48, v153
	v_ashrrev_i32_e32 v153, 31, v152
	v_lshl_add_u64 v[154:155], v[152:153], 2, s[44:45]
	global_load_dword v156, v[154:155], off
	s_ashr_i32 s13, s13, 3
	s_and_b32 s49, s13, -16
	s_or_b32 s13, s53, s74
	s_add_i32 s12, s49, s64
	s_lshl_b32 s55, s13, 10
	s_ashr_i32 s13, s12, 31
	s_lshl_b64 s[12:13], s[12:13], 14
	s_waitcnt vmcnt(0)
	v_div_scale_f32 v158, s[50:51], v156, v156, 1.0
	v_rcp_f32_e32 v159, v158
	s_add_i32 s50, s49, s48
	s_ashr_i32 s51, s50, 31
	s_lshl_b64 s[60:61], s[50:51], 14
	v_fma_f32 v166, -v158, v159, 1.0
	v_fmac_f32_e32 v159, v166, v159
	v_div_scale_f32 v166, vcc, 1.0, v156, 1.0
	v_mul_f32_e32 v167, v166, v159
	v_fma_f32 v168, -v158, v167, v166
	v_fmac_f32_e32 v167, v168, v159
	v_fma_f32 v158, -v158, v167, v166
	v_div_fmas_f32 v158, v158, v159, v167
	v_div_fixup_f32 v156, v158, v156, 1.0
	v_lshlrev_b32_e32 v158, 6, v152
	v_lshlrev_b32_e32 v159, 2, v152
	v_and_or_b32 v158, v158, s73, v165
	v_and_b32_e32 v159, 32, v159
	v_bitop3_b32 v174, v158, s55, v159 bitop3:0xde
	v_or_b32_e32 v158, s12, v174
	v_mov_b32_e32 v159, s13
	v_lshl_add_u64 v[166:167], s[40:41], 0, v[158:159]
	global_load_dwordx4 v[166:169], v[166:167], off nt
	s_waitcnt vmcnt(0)
	v_lshlrev_b32_e32 v170, 16, v166
	v_and_b32_e32 v171, 0xffff0000, v166
	v_lshlrev_b32_e32 v166, 16, v167
	v_and_b32_e32 v167, 0xffff0000, v167
	v_pk_mul_f32 v[170:171], v[156:157], v[170:171] op_sel_hi:[0,1]
	v_pk_mul_f32 v[166:167], v[156:157], v[166:167] op_sel_hi:[0,1]
	v_lshlrev_b32_e32 v172, 16, v168
	v_and_b32_e32 v173, 0xffff0000, v168
	v_lshlrev_b32_e32 v168, 16, v169
	v_and_b32_e32 v169, 0xffff0000, v169
	v_pk_mul_f32 v[172:173], v[156:157], v[172:173] op_sel_hi:[0,1]
	v_pk_mul_f32 v[168:169], v[156:157], v[168:169] op_sel_hi:[0,1]
	v_pk_fma_f32 v[128:129], v[146:147], v[166:167], v[128:129]
	v_pk_fma_f32 v[126:127], v[144:145], v[170:171], v[126:127]
	v_pk_fma_f32 v[166:167], v[150:151], v[168:169], v[124:125]
	v_pk_fma_f32 v[124:125], v[148:149], v[172:173], v[122:123]
	v_mul_f32_e32 v122, v127, v127
	v_mul_f32_e32 v123, v129, v129
	v_fmac_f32_e32 v122, v126, v126
	v_fmac_f32_e32 v123, v128, v128
	v_add_f32_e32 v122, v122, v123
	v_mul_f32_e32 v123, v125, v125
	v_fmac_f32_e32 v123, v124, v124
	v_add_f32_e32 v122, v123, v122
	v_mul_f32_e32 v123, v167, v167
	v_fmac_f32_e32 v123, v166, v166
	v_add_f32_e32 v168, v123, v122
	v_cvt_pk_bf16_f32 v122, v126, v127
	v_lshl_add_u64 v[126:127], s[42:43], 0, v[158:159]
	v_cvt_pk_bf16_f32 v123, v128, v129
	v_cvt_pk_bf16_f32 v124, v124, v125
	v_cvt_pk_bf16_f32 v125, v166, v167
	s_nop 0
	v_readfirstlane_b32 s98, v126
	v_readfirstlane_b32 s99, v127
	ds_write_b128 v216, v[122:125]
	ds_read_b128 v[220:223], v217
	v_or_b32_e32 v126, s60, v174
	v_mov_b32_e32 v127, s61
	v_lshl_add_u64 v[122:123], s[40:41], 0, v[126:127]
	global_load_dwordx4 v[122:125], v[122:123], off nt
	s_waitcnt vmcnt(0)
; __host__ __device__ __forceinline__ size_t img_off(int row, int col, int nkt) { return ((size_t)((row >> 7) * nkt + (col >> 6)) << 14) + (size_t)lds_byte(row & 127, col & 63); }
; __device__ __forceinline__ unsigned cvt_pk_bf16(float lo, float hi) { unsigned r; asm volatile("v_cvt_pk_bf16_f32 %0, %1, %2" : "=v"(r) : "v"(lo), "v"(hi)); return r; }
; __device__ __forceinline__ float quad_sum(float s) { s += __shfl_xor(s, 16); s += __shfl_xor(s, 32); return s; }
;     __device__ __forceinline__ void operator()(const f32x4 (&acc)[2][2][4][2], const Unit& u, int wr, int wc, int fr, int fq) const {
;     ...
;         for (int ai = 0; ai < 2; ++ai)
; #pragma unroll
;             for (int m = 0; m < 4; ++m) { const int row = row0 + ai * HALF + m * 16; float s = 0.f; const float rinv = 1.0f / rs[row];
; #pragma unroll
;                 for (int bj = 0; bj < 2; ++bj) { const u32x4 xw = __builtin_nontemporal_load((const u32x4*)(xn + img_off(row, col0 + bj * HALF, 16)));
;                     const f32x4 x0 = (f32x4){__builtin_bit_cast(float, xw.x << 16), __builtin_bit_cast(float, xw.x & 0xffff0000u), __builtin_bit_cast(float, xw.y << 16), __builtin_bit_cast(float, xw.y & 0xffff0000u)} * rinv * gi[bj][0];
;                     const f32x4 x1 = (f32x4){__builtin_bit_cast(float, xw.z << 16), __builtin_bit_cast(float, xw.z & 0xffff0000u), __builtin_bit_cast(float, xw.w << 16), __builtin_bit_cast(float, xw.w & 0xffff0000u)} * rinv * gi[bj][1];
;                     const f32x4 v0 = acc[ai][bj][m][0] + x0, v1 = acc[ai][bj][m][1] + x1;
;                     s += (v0[0] * v0[0] + v0[1] * v0[1]) + (v0[2] * v0[2] + v0[3] * v0[3]) + (v1[0] * v1[0] + v1[1] * v1[1]) + (v1[2] * v1[2] + v1[3] * v1[3]);
;                     u32x4 w; w.x = cvt_pk_bf16(v0[0], v0[1]); w.y = cvt_pk_bf16(v0[2], v0[3]); w.z = cvt_pk_bf16(v1[0], v1[1]); w.w = cvt_pk_bf16(v1[2], v1[3]);
;                     *(u32x4*)((char*)x1b + img_off(row, col0 + bj * HALF, 16)) = w; }
;                 s = quad_sum(s); if (fq == 0) atomicAdd(ss + row, s); }
	v_lshlrev_b32_e32 v128, 16, v122
	v_and_b32_e32 v129, 0xffff0000, v122
	v_lshlrev_b32_e32 v122, 16, v123
	v_and_b32_e32 v123, 0xffff0000, v123
	v_pk_mul_f32 v[128:129], v[156:157], v[128:129] op_sel_hi:[0,1]
	v_pk_mul_f32 v[122:123], v[156:157], v[122:123] op_sel_hi:[0,1]
	v_lshlrev_b32_e32 v158, 16, v124
	v_and_b32_e32 v159, 0xffff0000, v124
	v_lshlrev_b32_e32 v124, 16, v125
	v_and_b32_e32 v125, 0xffff0000, v125
	v_pk_mul_f32 v[158:159], v[156:157], v[158:159] op_sel_hi:[0,1]
	v_pk_mul_f32 v[124:125], v[156:157], v[124:125] op_sel_hi:[0,1]
	v_pk_fma_f32 v[120:121], v[136:137], v[122:123], v[120:121]
	v_pk_fma_f32 v[118:119], v[134:135], v[128:129], v[118:119]
	v_pk_fma_f32 v[122:123], v[132:133], v[124:125], v[116:117]
	v_pk_fma_f32 v[116:117], v[130:131], v[158:159], v[114:115]
	v_mul_f32_e32 v114, v119, v119
	v_mul_f32_e32 v115, v121, v121
	v_fmac_f32_e32 v114, v118, v118
	v_fmac_f32_e32 v115, v120, v120
	v_add_f32_e32 v114, v114, v115
	v_mul_f32_e32 v115, v117, v117
	v_fmac_f32_e32 v115, v116, v116
	v_add_f32_e32 v114, v115, v114
	v_mul_f32_e32 v115, v123, v123
	v_fmac_f32_e32 v115, v122, v122
	v_add_f32_e32 v114, v115, v114
	v_add_f32_e32 v124, v168, v114
	v_cvt_pk_bf16_f32 v114, v118, v119
	v_cvt_pk_bf16_f32 v115, v120, v121
	v_lshl_add_u64 v[118:119], s[42:43], 0, v[126:127]
	v_cvt_pk_bf16_f32 v116, v116, v117
	v_cvt_pk_bf16_f32 v117, v122, v123
	s_waitcnt lgkmcnt(0)
	global_store_dwordx4 v218, v[220:223], s[98:99]
	s_nop 0
	v_readfirstlane_b32 s98, v118
	v_readfirstlane_b32 s99, v119
	ds_write_b128 v216, v[114:117]
	ds_read_b128 v[220:223], v217
	s_nop 1
	v_and_b32_e32 v115, 64, v164
	v_xor_b32_e32 v114, 16, v164
	v_add_u32_e32 v115, 64, v115
	v_cmp_lt_i32_e32 vcc, v114, v115
	v_xor_b32_e32 v117, 32, v164
	s_nop 0
	v_cndmask_b32_e32 v114, v164, v114, vcc
	v_lshlrev_b32_e32 v116, 2, v114
	ds_bpermute_b32 v114, v116, v124
	v_cmp_lt_i32_e32 vcc, v117, v115
	s_waitcnt lgkmcnt(0)
	v_add_f32_e32 v114, v124, v114
	v_cndmask_b32_e32 v115, v164, v117, vcc
	v_lshlrev_b32_e32 v117, 2, v115
	ds_bpermute_b32 v115, v117, v114
	s_and_saveexec_b64 s[62:63], s[4:5]
	s_cbranch_execz .LBB0_886
	v_lshl_add_u64 v[118:119], v[152:153], 2, s[46:47]
	s_waitcnt lgkmcnt(0)
	v_add_f32_e32 v114, v114, v115
	global_atomic_add_f32 v[118:119], v114, off
.LBB0_886:
	s_or_b64 exec, exec, s[62:63]
	v_or_b32_e32 v114, 16, v152
	s_waitcnt lgkmcnt(0)
	v_ashrrev_i32_e32 v115, 31, v114
	v_lshl_add_u64 v[118:119], v[114:115], 2, s[44:45]
	global_load_dword v153, v[118:119], off
	v_lshrrev_b32_e32 v118, 3, v114
	v_and_or_b32 v119, v118, 10, s53
	v_lshlrev_b32_e32 v118, 6, v152
	v_lshlrev_b32_e32 v120, 10, v119
	v_lshlrev_b32_e32 v119, 2, v152
	v_and_or_b32 v118, v118, s73, v165
	v_and_b32_e32 v119, 32, v119
	v_bitop3_b32 v126, v118, v120, v119 bitop3:0xde
	v_or_b32_e32 v124, s12, v126
	v_mov_b32_e32 v125, s13
	v_lshl_add_u64 v[120:121], s[40:41], 0, v[124:125]
	global_load_dwordx4 v[120:123], v[120:121], off nt
	v_mov_b32_e32 v127, s61
	v_or_b32_e32 v126, s60, v126
	v_lshl_add_u64 v[124:125], s[42:43], 0, v[124:125]
	v_lshl_add_u64 v[128:129], s[40:41], 0, v[126:127]
	s_waitcnt vmcnt(1)
	v_div_scale_f32 v156, s[50:51], v153, v153, 1.0
	v_rcp_f32_e32 v169, v156
	v_div_scale_f32 v168, vcc, 1.0, v153, 1.0
	v_fma_f32 v170, -v156, v169, 1.0
	v_fmac_f32_e32 v169, v170, v169
	v_mul_f32_e32 v170, v168, v169
	v_fma_f32 v171, -v156, v170, v168
	v_fmac_f32_e32 v170, v171, v169
	v_fma_f32 v156, -v156, v170, v168
	v_div_fmas_f32 v156, v156, v169, v170
	s_waitcnt vmcnt(0)
	v_lshlrev_b32_e32 v158, 16, v120
	v_and_b32_e32 v159, 0xffff0000, v120
	v_lshlrev_b32_e32 v120, 16, v121
	v_and_b32_e32 v121, 0xffff0000, v121
	v_lshlrev_b32_e32 v166, 16, v122
	v_and_b32_e32 v167, 0xffff0000, v122
	v_lshlrev_b32_e32 v122, 16, v123
	v_and_b32_e32 v123, 0xffff0000, v123
	v_div_fixup_f32 v156, v156, v153, 1.0
	v_pk_mul_f32 v[158:159], v[156:157], v[158:159] op_sel_hi:[0,1]
	v_pk_mul_f32 v[120:121], v[156:157], v[120:121] op_sel_hi:[0,1]
	v_pk_mul_f32 v[166:167], v[156:157], v[166:167] op_sel_hi:[0,1]
	v_pk_mul_f32 v[122:123], v[156:157], v[122:123] op_sel_hi:[0,1]
	v_pk_fma_f32 v[112:113], v[146:147], v[120:121], v[112:113]
	v_pk_fma_f32 v[110:111], v[144:145], v[158:159], v[110:111]
	v_pk_fma_f32 v[120:121], v[150:151], v[122:123], v[108:109]
	v_pk_fma_f32 v[122:123], v[148:149], v[166:167], v[106:107]
	v_cvt_pk_bf16_f32 v106, v110, v111
	v_cvt_pk_bf16_f32 v107, v112, v113
	v_mul_f32_e32 v111, v111, v111
	v_cvt_pk_bf16_f32 v108, v122, v123
	v_cvt_pk_bf16_f32 v109, v120, v121
	s_waitcnt lgkmcnt(0)
	global_store_dwordx4 v218, v[220:223], s[98:99]
	s_nop 0
	v_readfirstlane_b32 s98, v124
	v_readfirstlane_b32 s99, v125
	ds_write_b128 v216, v[106:109]
	ds_read_b128 v[220:223], v217
	global_load_dwordx4 v[106:109], v[128:129], off nt
	v_mul_f32_e32 v113, v113, v113
	v_mul_f32_e32 v123, v123, v123
	v_fmac_f32_e32 v111, v110, v110
	v_fmac_f32_e32 v113, v112, v112
	v_mul_f32_e32 v121, v121, v121
	v_fmac_f32_e32 v123, v122, v122
	v_add_f32_e32 v110, v111, v113
	v_fmac_f32_e32 v121, v120, v120
	v_add_f32_e32 v110, v123, v110
	v_add_f32_e32 v120, v121, v110
	s_waitcnt vmcnt(0)
	v_lshlrev_b32_e32 v110, 16, v106
	v_and_b32_e32 v111, 0xffff0000, v106
	v_lshlrev_b32_e32 v106, 16, v107
	v_and_b32_e32 v107, 0xffff0000, v107
	v_lshlrev_b32_e32 v112, 16, v108
	v_and_b32_e32 v113, 0xffff0000, v108
	v_lshlrev_b32_e32 v108, 16, v109
	v_and_b32_e32 v109, 0xffff0000, v109
	v_pk_mul_f32 v[110:111], v[156:157], v[110:111] op_sel_hi:[0,1]
	v_pk_mul_f32 v[106:107], v[156:157], v[106:107] op_sel_hi:[0,1]
	v_pk_mul_f32 v[112:113], v[156:157], v[112:113] op_sel_hi:[0,1]
	v_pk_mul_f32 v[108:109], v[156:157], v[108:109] op_sel_hi:[0,1]
	v_pk_fma_f32 v[104:105], v[136:137], v[106:107], v[104:105]
	v_pk_fma_f32 v[102:103], v[134:135], v[110:111], v[102:103]
	v_pk_fma_f32 v[106:107], v[132:133], v[108:109], v[100:101]
	v_pk_fma_f32 v[108:109], v[130:131], v[112:113], v[98:99]
	v_mul_f32_e32 v98, v103, v103
	v_mul_f32_e32 v99, v105, v105
	v_mul_f32_e32 v100, v109, v109
	v_fmac_f32_e32 v98, v102, v102
	v_fmac_f32_e32 v99, v104, v104
	v_mul_f32_e32 v101, v107, v107
	v_fmac_f32_e32 v100, v108, v108
	v_add_f32_e32 v98, v98, v99
	v_add_f32_e32 v98, v100, v98
	v_fmac_f32_e32 v101, v106, v106
	v_add_f32_e32 v98, v101, v98
	v_add_f32_e32 v98, v120, v98
	ds_bpermute_b32 v99, v116, v98
	v_cvt_pk_bf16_f32 v100, v102, v103
	v_cvt_pk_bf16_f32 v101, v104, v105
	v_lshl_add_u64 v[104:105], s[42:43], 0, v[126:127]
	v_cvt_pk_bf16_f32 v102, v108, v109
	s_waitcnt lgkmcnt(0)
	v_add_f32_e32 v98, v98, v99
	ds_bpermute_b32 v99, v117, v98
	v_cvt_pk_bf16_f32 v103, v106, v107
	s_waitcnt lgkmcnt(0)
	global_store_dwordx4 v218, v[220:223], s[98:99]
	s_nop 0
	v_readfirstlane_b32 s98, v104
	v_readfirstlane_b32 s99, v105
	ds_write_b128 v216, v[100:103]
	ds_read_b128 v[220:223], v217
	s_and_saveexec_b64 s[62:63], s[4:5]
	s_cbranch_execz .LBB0_888
	v_lshl_add_u64 v[100:101], v[114:115], 2, s[46:47]
	s_waitcnt lgkmcnt(0)
	v_add_f32_e32 v98, v98, v99
	global_atomic_add_f32 v[100:101], v98, off
; __host__ __device__ __forceinline__ size_t img_off(int row, int col, int nkt) { return ((size_t)((row >> 7) * nkt + (col >> 6)) << 14) + (size_t)lds_byte(row & 127, col & 63); }
; __device__ __forceinline__ unsigned cvt_pk_bf16(float lo, float hi) { unsigned r; asm volatile("v_cvt_pk_bf16_f32 %0, %1, %2" : "=v"(r) : "v"(lo), "v"(hi)); return r; }
; __device__ __forceinline__ float quad_sum(float s) { s += __shfl_xor(s, 16); s += __shfl_xor(s, 32); return s; }
;     __device__ __forceinline__ void operator()(const f32x4 (&acc)[2][2][4][2], const Unit& u, int wr, int wc, int fr, int fq) const {
;     ...
;         for (int ai = 0; ai < 2; ++ai)
; #pragma unroll
;             for (int m = 0; m < 4; ++m) { const int row = row0 + ai * HALF + m * 16; float s = 0.f; const float rinv = 1.0f / rs[row];
; #pragma unroll
;                 for (int bj = 0; bj < 2; ++bj) { const u32x4 xw = __builtin_nontemporal_load((const u32x4*)(xn + img_off(row, col0 + bj * HALF, 16)));
;                     const f32x4 x0 = (f32x4){__builtin_bit_cast(float, xw.x << 16), __builtin_bit_cast(float, xw.x & 0xffff0000u), __builtin_bit_cast(float, xw.y << 16), __builtin_bit_cast(float, xw.y & 0xffff0000u)} * rinv * gi[bj][0];
;                     const f32x4 x1 = (f32x4){__builtin_bit_cast(float, xw.z << 16), __builtin_bit_cast(float, xw.z & 0xffff0000u), __builtin_bit_cast(float, xw.w << 16), __builtin_bit_cast(float, xw.w & 0xffff0000u)} * rinv * gi[bj][1];
;                     const f32x4 v0 = acc[ai][bj][m][0] + x0, v1 = acc[ai][bj][m][1] + x1;
;                     s += (v0[0] * v0[0] + v0[1] * v0[1]) + (v0[2] * v0[2] + v0[3] * v0[3]) + (v1[0] * v1[0] + v1[1] * v1[1]) + (v1[2] * v1[2] + v1[3] * v1[3]);
;                     u32x4 w; w.x = cvt_pk_bf16(v0[0], v0[1]); w.y = cvt_pk_bf16(v0[2], v0[3]); w.z = cvt_pk_bf16(v1[0], v1[1]); w.w = cvt_pk_bf16(v1[2], v1[3]);
;                     *(u32x4*)((char*)x1b + img_off(row, col0 + bj * HALF, 16)) = w; }
;                 s = quad_sum(s); if (fq == 0) atomicAdd(ss + row, s); }
.LBB0_888:
	s_or_b64 exec, exec, s[62:63]
	v_or_b32_e32 v98, 32, v152
	s_waitcnt lgkmcnt(0)
	v_ashrrev_i32_e32 v99, 31, v98
	v_lshl_add_u64 v[100:101], v[98:99], 2, s[44:45]
	global_load_dword v114, v[100:101], off
	v_lshrrev_b32_e32 v100, 3, v98
	v_and_or_b32 v100, v100, 12, s53
	v_lshlrev_b32_e32 v100, 10, v100
	v_bitop3_b32 v106, v118, v100, v119 bitop3:0xde
	v_or_b32_e32 v104, s12, v106
	v_mov_b32_e32 v105, s13
	v_lshl_add_u64 v[100:101], s[40:41], 0, v[104:105]
	global_load_dwordx4 v[100:103], v[100:101], off nt
	v_mov_b32_e32 v107, s61
	v_or_b32_e32 v106, s60, v106
	v_lshl_add_u64 v[104:105], s[42:43], 0, v[104:105]
	v_lshl_add_u64 v[108:109], s[40:41], 0, v[106:107]
	s_waitcnt vmcnt(1)
	v_div_scale_f32 v115, s[50:51], v114, v114, 1.0
	v_rcp_f32_e32 v121, v115
	v_div_scale_f32 v120, vcc, 1.0, v114, 1.0
	v_fma_f32 v122, -v115, v121, 1.0
	v_fmac_f32_e32 v121, v122, v121
	v_mul_f32_e32 v122, v120, v121
	v_fma_f32 v123, -v115, v122, v120
	v_fmac_f32_e32 v122, v123, v121
	v_fma_f32 v115, -v115, v122, v120
	v_div_fmas_f32 v115, v115, v121, v122
	s_waitcnt vmcnt(0)
	v_lshlrev_b32_e32 v110, 16, v100
	v_and_b32_e32 v111, 0xffff0000, v100
	v_lshlrev_b32_e32 v100, 16, v101
	v_and_b32_e32 v101, 0xffff0000, v101
	v_lshlrev_b32_e32 v112, 16, v102
	v_and_b32_e32 v113, 0xffff0000, v102
	v_lshlrev_b32_e32 v102, 16, v103
	v_and_b32_e32 v103, 0xffff0000, v103
	v_div_fixup_f32 v114, v115, v114, 1.0
	v_pk_mul_f32 v[110:111], v[114:115], v[110:111] op_sel_hi:[0,1]
	v_pk_mul_f32 v[100:101], v[114:115], v[100:101] op_sel_hi:[0,1]
	v_pk_mul_f32 v[112:113], v[114:115], v[112:113] op_sel_hi:[0,1]
	v_pk_mul_f32 v[102:103], v[114:115], v[102:103] op_sel_hi:[0,1]
	v_pk_fma_f32 v[96:97], v[146:147], v[100:101], v[96:97]
	v_pk_fma_f32 v[94:95], v[144:145], v[110:111], v[94:95]
	v_pk_fma_f32 v[100:101], v[150:151], v[102:103], v[92:93]
	v_pk_fma_f32 v[102:103], v[148:149], v[112:113], v[90:91]
	v_cvt_pk_bf16_f32 v90, v94, v95
	v_cvt_pk_bf16_f32 v91, v96, v97
	v_mul_f32_e32 v95, v95, v95
	v_cvt_pk_bf16_f32 v92, v102, v103
	v_cvt_pk_bf16_f32 v93, v100, v101
	s_waitcnt lgkmcnt(0)
	global_store_dwordx4 v218, v[220:223], s[98:99]
	s_nop 0
	v_readfirstlane_b32 s98, v104
	v_readfirstlane_b32 s99, v105
	ds_write_b128 v216, v[90:93]
	ds_read_b128 v[220:223], v217
	global_load_dwordx4 v[90:93], v[108:109], off nt
	v_mul_f32_e32 v97, v97, v97
	v_mul_f32_e32 v103, v103, v103
	v_fmac_f32_e32 v95, v94, v94
	v_fmac_f32_e32 v97, v96, v96
	v_mul_f32_e32 v101, v101, v101
	v_fmac_f32_e32 v103, v102, v102
	v_add_f32_e32 v94, v95, v97
	v_fmac_f32_e32 v101, v100, v100
	v_add_f32_e32 v94, v103, v94
	v_add_f32_e32 v100, v101, v94
	s_waitcnt vmcnt(0)
	v_lshlrev_b32_e32 v94, 16, v90
	v_and_b32_e32 v95, 0xffff0000, v90
	v_lshlrev_b32_e32 v90, 16, v91
	v_and_b32_e32 v91, 0xffff0000, v91
	v_lshlrev_b32_e32 v96, 16, v92
	v_and_b32_e32 v97, 0xffff0000, v92
	v_lshlrev_b32_e32 v92, 16, v93
	v_and_b32_e32 v93, 0xffff0000, v93
	v_pk_mul_f32 v[94:95], v[114:115], v[94:95] op_sel_hi:[0,1]
	v_pk_mul_f32 v[90:91], v[114:115], v[90:91] op_sel_hi:[0,1]
	v_pk_mul_f32 v[96:97], v[114:115], v[96:97] op_sel_hi:[0,1]
	v_pk_mul_f32 v[92:93], v[114:115], v[92:93] op_sel_hi:[0,1]
	v_pk_fma_f32 v[88:89], v[136:137], v[90:91], v[88:89]
	v_pk_fma_f32 v[86:87], v[134:135], v[94:95], v[86:87]
	v_pk_fma_f32 v[90:91], v[132:133], v[92:93], v[84:85]
	v_pk_fma_f32 v[92:93], v[130:131], v[96:97], v[82:83]
	v_mul_f32_e32 v82, v87, v87
	v_mul_f32_e32 v83, v89, v89
	v_mul_f32_e32 v84, v93, v93
	v_fmac_f32_e32 v82, v86, v86
	v_fmac_f32_e32 v83, v88, v88
	v_mul_f32_e32 v85, v91, v91
	v_fmac_f32_e32 v84, v92, v92
	v_add_f32_e32 v82, v82, v83
	v_add_f32_e32 v82, v84, v82
	v_fmac_f32_e32 v85, v90, v90
	v_add_f32_e32 v82, v85, v82
	v_add_f32_e32 v82, v100, v82
	ds_bpermute_b32 v83, v116, v82
	v_cvt_pk_bf16_f32 v84, v86, v87
	v_cvt_pk_bf16_f32 v85, v88, v89
	v_lshl_add_u64 v[88:89], s[42:43], 0, v[106:107]
	v_cvt_pk_bf16_f32 v86, v92, v93
	s_waitcnt lgkmcnt(0)
	v_add_f32_e32 v82, v82, v83
	ds_bpermute_b32 v83, v117, v82
	v_cvt_pk_bf16_f32 v87, v90, v91
	s_waitcnt lgkmcnt(0)
	global_store_dwordx4 v218, v[220:223], s[98:99]
	s_nop 0
	v_readfirstlane_b32 s98, v88
	v_readfirstlane_b32 s99, v89
	ds_write_b128 v216, v[84:87]
	ds_read_b128 v[220:223], v217
	s_and_saveexec_b64 s[62:63], s[4:5]
	v_readlane_b32 s84, v251, 53
	v_readlane_b32 s85, v251, 54
	s_mov_b64 s[92:93], s[18:19]
	s_cbranch_execz .LBB0_890
	v_lshl_add_u64 v[84:85], v[98:99], 2, s[46:47]
	s_waitcnt lgkmcnt(0)
	v_add_f32_e32 v82, v82, v83
	global_atomic_add_f32 v[84:85], v82, off
; __host__ __device__ __forceinline__ size_t img_off(int row, int col, int nkt) { return ((size_t)((row >> 7) * nkt + (col >> 6)) << 14) + (size_t)lds_byte(row & 127, col & 63); }
; __device__ __forceinline__ unsigned cvt_pk_bf16(float lo, float hi) { unsigned r; asm volatile("v_cvt_pk_bf16_f32 %0, %1, %2" : "=v"(r) : "v"(lo), "v"(hi)); return r; }
; __device__ __forceinline__ float quad_sum(float s) { s += __shfl_xor(s, 16); s += __shfl_xor(s, 32); return s; }
;     __device__ __forceinline__ void operator()(const f32x4 (&acc)[2][2][4][2], const Unit& u, int wr, int wc, int fr, int fq) const {
;     ...
;         for (int ai = 0; ai < 2; ++ai)
; #pragma unroll
;             for (int m = 0; m < 4; ++m) { const int row = row0 + ai * HALF + m * 16; float s = 0.f; const float rinv = 1.0f / rs[row];
; #pragma unroll
;                 for (int bj = 0; bj < 2; ++bj) { const u32x4 xw = __builtin_nontemporal_load((const u32x4*)(xn + img_off(row, col0 + bj * HALF, 16)));
;                     const f32x4 x0 = (f32x4){__builtin_bit_cast(float, xw.x << 16), __builtin_bit_cast(float, xw.x & 0xffff0000u), __builtin_bit_cast(float, xw.y << 16), __builtin_bit_cast(float, xw.y & 0xffff0000u)} * rinv * gi[bj][0];
;                     const f32x4 x1 = (f32x4){__builtin_bit_cast(float, xw.z << 16), __builtin_bit_cast(float, xw.z & 0xffff0000u), __builtin_bit_cast(float, xw.w << 16), __builtin_bit_cast(float, xw.w & 0xffff0000u)} * rinv * gi[bj][1];
;                     const f32x4 v0 = acc[ai][bj][m][0] + x0, v1 = acc[ai][bj][m][1] + x1;
;                     s += (v0[0] * v0[0] + v0[1] * v0[1]) + (v0[2] * v0[2] + v0[3] * v0[3]) + (v1[0] * v1[0] + v1[1] * v1[1]) + (v1[2] * v1[2] + v1[3] * v1[3]);
;                     u32x4 w; w.x = cvt_pk_bf16(v0[0], v0[1]); w.y = cvt_pk_bf16(v0[2], v0[3]); w.z = cvt_pk_bf16(v1[0], v1[1]); w.w = cvt_pk_bf16(v1[2], v1[3]);
;                     *(u32x4*)((char*)x1b + img_off(row, col0 + bj * HALF, 16)) = w; }
;                 s = quad_sum(s); if (fq == 0) atomicAdd(ss + row, s); }
.LBB0_890:
	s_or_b64 exec, exec, s[62:63]
	v_or_b32_e32 v82, 48, v152
	s_waitcnt lgkmcnt(0)
	v_ashrrev_i32_e32 v83, 31, v82
	v_lshl_add_u64 v[84:85], v[82:83], 2, s[44:45]
	global_load_dword v98, v[84:85], off
	v_lshrrev_b32_e32 v84, 3, v82
	v_and_or_b32 v84, v84, 14, s53
	v_lshlrev_b32_e32 v84, 10, v84
	v_bitop3_b32 v90, v118, v84, v119 bitop3:0xde
	v_or_b32_e32 v88, s12, v90
	v_mov_b32_e32 v89, s13
	v_lshl_add_u64 v[84:85], s[40:41], 0, v[88:89]
	global_load_dwordx4 v[84:87], v[84:85], off nt
	v_mov_b32_e32 v91, s61
	v_or_b32_e32 v90, s60, v90
	v_lshl_add_u64 v[88:89], s[42:43], 0, v[88:89]
	v_lshl_add_u64 v[92:93], s[40:41], 0, v[90:91]
	s_waitcnt vmcnt(1)
	v_div_scale_f32 v99, s[12:13], v98, v98, 1.0
	v_rcp_f32_e32 v101, v99
	v_div_scale_f32 v100, vcc, 1.0, v98, 1.0
	v_fma_f32 v102, -v99, v101, 1.0
	v_fmac_f32_e32 v101, v102, v101
	v_mul_f32_e32 v102, v100, v101
	v_fma_f32 v103, -v99, v102, v100
	v_fmac_f32_e32 v102, v103, v101
	v_fma_f32 v99, -v99, v102, v100
	v_div_fmas_f32 v99, v99, v101, v102
	s_waitcnt vmcnt(0)
	v_lshlrev_b32_e32 v94, 16, v84
	v_and_b32_e32 v95, 0xffff0000, v84
	v_lshlrev_b32_e32 v84, 16, v85
	v_and_b32_e32 v85, 0xffff0000, v85
	v_lshlrev_b32_e32 v96, 16, v86
	v_and_b32_e32 v97, 0xffff0000, v86
	v_lshlrev_b32_e32 v86, 16, v87
	v_and_b32_e32 v87, 0xffff0000, v87
	v_div_fixup_f32 v98, v99, v98, 1.0
	v_pk_mul_f32 v[94:95], v[98:99], v[94:95] op_sel_hi:[0,1]
	v_pk_mul_f32 v[84:85], v[98:99], v[84:85] op_sel_hi:[0,1]
	v_pk_mul_f32 v[96:97], v[98:99], v[96:97] op_sel_hi:[0,1]
	v_pk_mul_f32 v[86:87], v[98:99], v[86:87] op_sel_hi:[0,1]
	v_pk_fma_f32 v[80:81], v[146:147], v[84:85], v[80:81]
	v_pk_fma_f32 v[78:79], v[144:145], v[94:95], v[78:79]
	v_pk_fma_f32 v[84:85], v[150:151], v[86:87], v[76:77]
	v_pk_fma_f32 v[86:87], v[148:149], v[96:97], v[74:75]
	v_cvt_pk_bf16_f32 v74, v78, v79
	v_cvt_pk_bf16_f32 v75, v80, v81
	v_mul_f32_e32 v79, v79, v79
	v_cvt_pk_bf16_f32 v76, v86, v87
	v_cvt_pk_bf16_f32 v77, v84, v85
	s_waitcnt lgkmcnt(0)
	global_store_dwordx4 v218, v[220:223], s[98:99]
	s_nop 0
	v_readfirstlane_b32 s98, v88
	v_readfirstlane_b32 s99, v89
	ds_write_b128 v216, v[74:77]
	ds_read_b128 v[220:223], v217
	global_load_dwordx4 v[74:77], v[92:93], off nt
	v_mul_f32_e32 v81, v81, v81
	v_mul_f32_e32 v87, v87, v87
	v_fmac_f32_e32 v79, v78, v78
	v_fmac_f32_e32 v81, v80, v80
	v_mul_f32_e32 v85, v85, v85
	v_fmac_f32_e32 v87, v86, v86
	v_add_f32_e32 v78, v79, v81
	v_fmac_f32_e32 v85, v84, v84
	v_add_f32_e32 v78, v87, v78
	v_add_f32_e32 v84, v85, v78
	s_waitcnt vmcnt(0)
	v_lshlrev_b32_e32 v78, 16, v74
	v_and_b32_e32 v79, 0xffff0000, v74
	v_lshlrev_b32_e32 v74, 16, v75
	v_and_b32_e32 v75, 0xffff0000, v75
	v_lshlrev_b32_e32 v80, 16, v76
	v_and_b32_e32 v81, 0xffff0000, v76
	v_lshlrev_b32_e32 v76, 16, v77
	v_and_b32_e32 v77, 0xffff0000, v77
	v_pk_mul_f32 v[78:79], v[98:99], v[78:79] op_sel_hi:[0,1]
	v_pk_mul_f32 v[74:75], v[98:99], v[74:75] op_sel_hi:[0,1]
	v_pk_mul_f32 v[80:81], v[98:99], v[80:81] op_sel_hi:[0,1]
	v_pk_mul_f32 v[76:77], v[98:99], v[76:77] op_sel_hi:[0,1]
	v_pk_fma_f32 v[72:73], v[136:137], v[74:75], v[72:73]
	v_pk_fma_f32 v[70:71], v[134:135], v[78:79], v[70:71]
	v_pk_fma_f32 v[74:75], v[132:133], v[76:77], v[68:69]
	v_pk_fma_f32 v[76:77], v[130:131], v[80:81], v[66:67]
	v_mul_f32_e32 v66, v71, v71
	v_mul_f32_e32 v67, v73, v73
	v_mul_f32_e32 v68, v77, v77
	v_fmac_f32_e32 v66, v70, v70
	v_fmac_f32_e32 v67, v72, v72
	v_mul_f32_e32 v69, v75, v75
	v_fmac_f32_e32 v68, v76, v76
	v_add_f32_e32 v66, v66, v67
	v_add_f32_e32 v66, v68, v66
	v_fmac_f32_e32 v69, v74, v74
	v_add_f32_e32 v66, v69, v66
	v_add_f32_e32 v66, v84, v66
	ds_bpermute_b32 v67, v116, v66
	v_cvt_pk_bf16_f32 v68, v70, v71
	v_cvt_pk_bf16_f32 v69, v72, v73
	v_lshl_add_u64 v[72:73], s[42:43], 0, v[90:91]
	v_cvt_pk_bf16_f32 v70, v76, v77
	s_waitcnt lgkmcnt(0)
	v_add_f32_e32 v66, v66, v67
	ds_bpermute_b32 v67, v117, v66
	v_cvt_pk_bf16_f32 v71, v74, v75
	s_waitcnt lgkmcnt(0)
	global_store_dwordx4 v218, v[220:223], s[98:99]
	s_nop 0
	v_readfirstlane_b32 s98, v72
	v_readfirstlane_b32 s99, v73
	ds_write_b128 v216, v[68:71]
	ds_read_b128 v[220:223], v217
	s_and_saveexec_b64 s[12:13], s[4:5]
	s_cbranch_execz .LBB0_892
	v_lshl_add_u64 v[68:69], v[82:83], 2, s[46:47]
	s_waitcnt lgkmcnt(0)
	v_add_f32_e32 v66, v66, v67
	global_atomic_add_f32 v[68:69], v66, off
; __host__ __device__ __forceinline__ size_t img_off(int row, int col, int nkt) { return ((size_t)((row >> 7) * nkt + (col >> 6)) << 14) + (size_t)lds_byte(row & 127, col & 63); }
; __device__ __forceinline__ unsigned cvt_pk_bf16(float lo, float hi) { unsigned r; asm volatile("v_cvt_pk_bf16_f32 %0, %1, %2" : "=v"(r) : "v"(lo), "v"(hi)); return r; }
; __device__ __forceinline__ float quad_sum(float s) { s += __shfl_xor(s, 16); s += __shfl_xor(s, 32); return s; }
;     __device__ __forceinline__ void operator()(const f32x4 (&acc)[2][2][4][2], const Unit& u, int wr, int wc, int fr, int fq) const {
;     ...
;         for (int ai = 0; ai < 2; ++ai)
; #pragma unroll
;             for (int m = 0; m < 4; ++m) { const int row = row0 + ai * HALF + m * 16; float s = 0.f; const float rinv = 1.0f / rs[row];
; #pragma unroll
;                 for (int bj = 0; bj < 2; ++bj) { const u32x4 xw = __builtin_nontemporal_load((const u32x4*)(xn + img_off(row, col0 + bj * HALF, 16)));
;                     const f32x4 x0 = (f32x4){__builtin_bit_cast(float, xw.x << 16), __builtin_bit_cast(float, xw.x & 0xffff0000u), __builtin_bit_cast(float, xw.y << 16), __builtin_bit_cast(float, xw.y & 0xffff0000u)} * rinv * gi[bj][0];
;                     const f32x4 x1 = (f32x4){__builtin_bit_cast(float, xw.z << 16), __builtin_bit_cast(float, xw.z & 0xffff0000u), __builtin_bit_cast(float, xw.w << 16), __builtin_bit_cast(float, xw.w & 0xffff0000u)} * rinv * gi[bj][1];
;                     const f32x4 v0 = acc[ai][bj][m][0] + x0, v1 = acc[ai][bj][m][1] + x1;
;                     s += (v0[0] * v0[0] + v0[1] * v0[1]) + (v0[2] * v0[2] + v0[3] * v0[3]) + (v1[0] * v1[0] + v1[1] * v1[1]) + (v1[2] * v1[2] + v1[3] * v1[3]);
;                     u32x4 w; w.x = cvt_pk_bf16(v0[0], v0[1]); w.y = cvt_pk_bf16(v0[2], v0[3]); w.z = cvt_pk_bf16(v1[0], v1[1]); w.w = cvt_pk_bf16(v1[2], v1[3]);
;                     *(u32x4*)((char*)x1b + img_off(row, col0 + bj * HALF, 16)) = w; }
;                 s = quad_sum(s); if (fq == 0) atomicAdd(ss + row, s); }
.LBB0_892:
	s_or_b64 exec, exec, s[12:13]
	global_load_dword v86, v[154:155], off offset:512
	v_add_u32_e32 v70, 0x80, v152
	v_ashrrev_i32_e32 v66, 3, v70
	v_and_b32_e32 v71, -16, v66
	v_lshlrev_b32_e32 v66, 6, v70
	s_waitcnt lgkmcnt(0)
	v_lshlrev_b32_e32 v67, 2, v70
	v_and_or_b32 v66, v66, s73, v165
	v_and_b32_e32 v67, 32, v67
	v_bitop3_b32 v78, v66, s55, v67 bitop3:0xde
	v_add_u32_e32 v66, s64, v71
	v_ashrrev_i32_e32 v67, 31, v66
	v_lshlrev_b64 v[68:69], 14, v[66:67]
	v_or_b32_e32 v76, v68, v78
	v_mov_b32_e32 v77, v69
	v_lshl_add_u64 v[66:67], s[40:41], 0, v[76:77]
	global_load_dwordx4 v[72:75], v[66:67], off nt
	v_add_u32_e32 v66, s48, v71
	v_ashrrev_i32_e32 v67, 31, v66
	v_lshlrev_b64 v[66:67], 14, v[66:67]
	v_or_b32_e32 v78, v66, v78
	v_mov_b32_e32 v79, v67
	v_lshl_add_u64 v[76:77], s[42:43], 0, v[76:77]
	v_lshl_add_u64 v[80:81], s[40:41], 0, v[78:79]
	s_waitcnt vmcnt(1)
	v_div_scale_f32 v71, s[12:13], v86, v86, 1.0
	v_rcp_f32_e32 v87, v71
	v_div_scale_f32 v88, vcc, 1.0, v86, 1.0
	v_fma_f32 v82, -v71, v87, 1.0
	v_fmac_f32_e32 v87, v82, v87
	v_mul_f32_e32 v89, v88, v87
	v_fma_f32 v90, -v71, v89, v88
	v_fmac_f32_e32 v89, v90, v87
	v_fma_f32 v71, -v71, v89, v88
	v_div_fmas_f32 v71, v71, v87, v89
	v_div_fixup_f32 v86, v71, v86, 1.0
	s_waitcnt vmcnt(0)
	v_lshlrev_b32_e32 v82, 16, v72
	v_and_b32_e32 v83, 0xffff0000, v72
	v_lshlrev_b32_e32 v72, 16, v73
	v_and_b32_e32 v73, 0xffff0000, v73
	v_lshlrev_b32_e32 v84, 16, v74
	v_and_b32_e32 v85, 0xffff0000, v74
	v_lshlrev_b32_e32 v74, 16, v75
	v_and_b32_e32 v75, 0xffff0000, v75
	v_pk_mul_f32 v[82:83], v[86:87], v[82:83] op_sel_hi:[0,1]
	v_pk_mul_f32 v[72:73], v[86:87], v[72:73] op_sel_hi:[0,1]
	v_pk_mul_f32 v[84:85], v[86:87], v[84:85] op_sel_hi:[0,1]
	v_pk_mul_f32 v[74:75], v[86:87], v[74:75] op_sel_hi:[0,1]
	v_pk_fma_f32 v[64:65], v[146:147], v[72:73], v[64:65]
	v_pk_fma_f32 v[62:63], v[144:145], v[82:83], v[62:63]
	v_pk_fma_f32 v[72:73], v[150:151], v[74:75], v[60:61]
	v_pk_fma_f32 v[74:75], v[148:149], v[84:85], v[58:59]
	v_cvt_pk_bf16_f32 v58, v62, v63
	v_cvt_pk_bf16_f32 v59, v64, v65
	v_mul_f32_e32 v63, v63, v63
	v_cvt_pk_bf16_f32 v60, v74, v75
	v_cvt_pk_bf16_f32 v61, v72, v73
	s_waitcnt lgkmcnt(0)
	global_store_dwordx4 v218, v[220:223], s[98:99]
	s_nop 0
	v_readfirstlane_b32 s98, v76
	v_readfirstlane_b32 s99, v77
	ds_write_b128 v216, v[58:61]
	ds_read_b128 v[220:223], v217
	global_load_dwordx4 v[58:61], v[80:81], off nt
	v_mul_f32_e32 v65, v65, v65
	v_mul_f32_e32 v71, v75, v75
	v_fmac_f32_e32 v63, v62, v62
	v_fmac_f32_e32 v65, v64, v64
	v_mul_f32_e32 v73, v73, v73
	v_fmac_f32_e32 v71, v74, v74
	v_add_f32_e32 v62, v63, v65
	v_fmac_f32_e32 v73, v72, v72
	v_add_f32_e32 v62, v71, v62
	v_add_f32_e32 v71, v73, v62
	s_waitcnt vmcnt(0)
	v_lshlrev_b32_e32 v62, 16, v58
	v_and_b32_e32 v63, 0xffff0000, v58
	v_lshlrev_b32_e32 v58, 16, v59
	v_and_b32_e32 v59, 0xffff0000, v59
	v_lshlrev_b32_e32 v64, 16, v60
	v_and_b32_e32 v65, 0xffff0000, v60
	v_lshlrev_b32_e32 v60, 16, v61
	v_and_b32_e32 v61, 0xffff0000, v61
	v_pk_mul_f32 v[62:63], v[86:87], v[62:63] op_sel_hi:[0,1]
	v_pk_mul_f32 v[58:59], v[86:87], v[58:59] op_sel_hi:[0,1]
	v_pk_mul_f32 v[64:65], v[86:87], v[64:65] op_sel_hi:[0,1]
	v_pk_mul_f32 v[60:61], v[86:87], v[60:61] op_sel_hi:[0,1]
	v_pk_fma_f32 v[56:57], v[136:137], v[58:59], v[56:57]
	v_pk_fma_f32 v[54:55], v[134:135], v[62:63], v[54:55]
	v_pk_fma_f32 v[58:59], v[132:133], v[60:61], v[52:53]
	v_pk_fma_f32 v[60:61], v[130:131], v[64:65], v[50:51]
	v_mul_f32_e32 v50, v55, v55
	v_mul_f32_e32 v51, v57, v57
	v_mul_f32_e32 v52, v61, v61
	v_fmac_f32_e32 v50, v54, v54
	v_fmac_f32_e32 v51, v56, v56
	v_mul_f32_e32 v53, v59, v59
	v_fmac_f32_e32 v52, v60, v60
	v_add_f32_e32 v50, v50, v51
	v_add_f32_e32 v50, v52, v50
	v_fmac_f32_e32 v53, v58, v58
	v_add_f32_e32 v50, v53, v50
	v_add_f32_e32 v50, v71, v50
	ds_bpermute_b32 v51, v116, v50
	v_cvt_pk_bf16_f32 v52, v54, v55
	v_cvt_pk_bf16_f32 v53, v56, v57
	v_lshl_add_u64 v[56:57], s[42:43], 0, v[78:79]
	v_cvt_pk_bf16_f32 v54, v60, v61
	s_waitcnt lgkmcnt(0)
	v_add_f32_e32 v50, v50, v51
	ds_bpermute_b32 v51, v117, v50
	v_cvt_pk_bf16_f32 v55, v58, v59
	s_waitcnt lgkmcnt(0)
	global_store_dwordx4 v218, v[220:223], s[98:99]
	s_nop 0
	v_readfirstlane_b32 s98, v56
	v_readfirstlane_b32 s99, v57
	ds_write_b128 v216, v[52:55]
	ds_read_b128 v[220:223], v217
	s_and_saveexec_b64 s[12:13], s[4:5]
	s_cbranch_execz .LBB0_894
	v_ashrrev_i32_e32 v71, 31, v70
	v_lshl_add_u64 v[52:53], v[70:71], 2, s[46:47]
	s_waitcnt lgkmcnt(0)
	v_add_f32_e32 v50, v50, v51
	global_atomic_add_f32 v[52:53], v50, off
; __host__ __device__ __forceinline__ size_t img_off(int row, int col, int nkt) { return ((size_t)((row >> 7) * nkt + (col >> 6)) << 14) + (size_t)lds_byte(row & 127, col & 63); }
; __device__ __forceinline__ unsigned cvt_pk_bf16(float lo, float hi) { unsigned r; asm volatile("v_cvt_pk_bf16_f32 %0, %1, %2" : "=v"(r) : "v"(lo), "v"(hi)); return r; }
; __device__ __forceinline__ float quad_sum(float s) { s += __shfl_xor(s, 16); s += __shfl_xor(s, 32); return s; }
;     __device__ __forceinline__ void operator()(const f32x4 (&acc)[2][2][4][2], const Unit& u, int wr, int wc, int fr, int fq) const {
;     ...
;         for (int ai = 0; ai < 2; ++ai)
; #pragma unroll
;             for (int m = 0; m < 4; ++m) { const int row = row0 + ai * HALF + m * 16; float s = 0.f; const float rinv = 1.0f / rs[row];
; #pragma unroll
;                 for (int bj = 0; bj < 2; ++bj) { const u32x4 xw = __builtin_nontemporal_load((const u32x4*)(xn + img_off(row, col0 + bj * HALF, 16)));
;                     const f32x4 x0 = (f32x4){__builtin_bit_cast(float, xw.x << 16), __builtin_bit_cast(float, xw.x & 0xffff0000u), __builtin_bit_cast(float, xw.y << 16), __builtin_bit_cast(float, xw.y & 0xffff0000u)} * rinv * gi[bj][0];
;                     const f32x4 x1 = (f32x4){__builtin_bit_cast(float, xw.z << 16), __builtin_bit_cast(float, xw.z & 0xffff0000u), __builtin_bit_cast(float, xw.w << 16), __builtin_bit_cast(float, xw.w & 0xffff0000u)} * rinv * gi[bj][1];
;                     const f32x4 v0 = acc[ai][bj][m][0] + x0, v1 = acc[ai][bj][m][1] + x1;
;                     s += (v0[0] * v0[0] + v0[1] * v0[1]) + (v0[2] * v0[2] + v0[3] * v0[3]) + (v1[0] * v1[0] + v1[1] * v1[1]) + (v1[2] * v1[2] + v1[3] * v1[3]);
;                     u32x4 w; w.x = cvt_pk_bf16(v0[0], v0[1]); w.y = cvt_pk_bf16(v0[2], v0[3]); w.z = cvt_pk_bf16(v1[0], v1[1]); w.w = cvt_pk_bf16(v1[2], v1[3]);
;                     *(u32x4*)((char*)x1b + img_off(row, col0 + bj * HALF, 16)) = w; }
;                 s = quad_sum(s); if (fq == 0) atomicAdd(ss + row, s); }
.LBB0_894:
	s_or_b64 exec, exec, s[12:13]
	s_waitcnt lgkmcnt(0)
	global_load_dword v51, v[154:155], off offset:576
	v_add_u32_e32 v50, 0x90, v152
	v_lshrrev_b32_e32 v52, 3, v50
	v_and_or_b32 v52, v52, 10, s53
	v_lshlrev_b32_e32 v53, 6, v50
	v_lshlrev_b32_e32 v54, 2, v50
	v_and_or_b32 v53, v53, s73, v165
	v_lshlrev_b32_e32 v52, 10, v52
	v_and_b32_e32 v54, 32, v54
	v_bitop3_b32 v58, v53, v52, v54 bitop3:0xde
	v_or_b32_e32 v56, v68, v58
	v_mov_b32_e32 v57, v69
	v_lshl_add_u64 v[52:53], s[40:41], 0, v[56:57]
	global_load_dwordx4 v[52:55], v[52:53], off nt
	v_mov_b32_e32 v59, v67
	v_or_b32_e32 v58, v66, v58
	v_lshl_add_u64 v[56:57], s[42:43], 0, v[56:57]
	v_lshl_add_u64 v[60:61], s[40:41], 0, v[58:59]
	s_waitcnt vmcnt(1)
	v_div_scale_f32 v70, s[12:13], v51, v51, 1.0
	v_rcp_f32_e32 v71, v70
	v_div_scale_f32 v72, vcc, 1.0, v51, 1.0
	v_fma_f32 v62, -v70, v71, 1.0
	v_fmac_f32_e32 v71, v62, v71
	v_mul_f32_e32 v73, v72, v71
	v_fma_f32 v74, -v70, v73, v72
	v_fmac_f32_e32 v73, v74, v71
	v_fma_f32 v70, -v70, v73, v72
	v_div_fmas_f32 v70, v70, v71, v73
	s_waitcnt vmcnt(0)
	v_lshlrev_b32_e32 v62, 16, v52
	v_and_b32_e32 v63, 0xffff0000, v52
	v_lshlrev_b32_e32 v52, 16, v53
	v_and_b32_e32 v53, 0xffff0000, v53
	v_lshlrev_b32_e32 v64, 16, v54
	v_and_b32_e32 v65, 0xffff0000, v54
	v_lshlrev_b32_e32 v54, 16, v55
	v_and_b32_e32 v55, 0xffff0000, v55
	v_div_fixup_f32 v70, v70, v51, 1.0
	v_pk_mul_f32 v[62:63], v[70:71], v[62:63] op_sel_hi:[0,1]
	v_pk_mul_f32 v[52:53], v[70:71], v[52:53] op_sel_hi:[0,1]
	v_pk_mul_f32 v[64:65], v[70:71], v[64:65] op_sel_hi:[0,1]
	v_pk_mul_f32 v[54:55], v[70:71], v[54:55] op_sel_hi:[0,1]
	v_pk_fma_f32 v[48:49], v[146:147], v[52:53], v[48:49]
	v_pk_fma_f32 v[46:47], v[144:145], v[62:63], v[46:47]
	v_pk_fma_f32 v[52:53], v[150:151], v[54:55], v[44:45]
	v_pk_fma_f32 v[54:55], v[148:149], v[64:65], v[42:43]
	v_cvt_pk_bf16_f32 v42, v46, v47
	v_cvt_pk_bf16_f32 v43, v48, v49
	v_mul_f32_e32 v47, v47, v47
	v_cvt_pk_bf16_f32 v44, v54, v55
	v_cvt_pk_bf16_f32 v45, v52, v53
	s_waitcnt lgkmcnt(0)
	global_store_dwordx4 v218, v[220:223], s[98:99]
	s_nop 0
	v_readfirstlane_b32 s98, v56
	v_readfirstlane_b32 s99, v57
	ds_write_b128 v216, v[42:45]
	ds_read_b128 v[220:223], v217
	global_load_dwordx4 v[42:45], v[60:61], off nt
	v_mul_f32_e32 v49, v49, v49
	v_mul_f32_e32 v51, v55, v55
	v_fmac_f32_e32 v47, v46, v46
	v_fmac_f32_e32 v49, v48, v48
	v_mul_f32_e32 v53, v53, v53
	v_fmac_f32_e32 v51, v54, v54
	v_add_f32_e32 v46, v47, v49
	v_fmac_f32_e32 v53, v52, v52
	v_add_f32_e32 v46, v51, v46
	v_add_f32_e32 v51, v53, v46
	s_waitcnt vmcnt(0)
	v_lshlrev_b32_e32 v46, 16, v42
	v_and_b32_e32 v47, 0xffff0000, v42
	v_lshlrev_b32_e32 v42, 16, v43
	v_and_b32_e32 v43, 0xffff0000, v43
	v_lshlrev_b32_e32 v48, 16, v44
	v_and_b32_e32 v49, 0xffff0000, v44
	v_lshlrev_b32_e32 v44, 16, v45
	v_and_b32_e32 v45, 0xffff0000, v45
	v_pk_mul_f32 v[46:47], v[70:71], v[46:47] op_sel_hi:[0,1]
	v_pk_mul_f32 v[42:43], v[70:71], v[42:43] op_sel_hi:[0,1]
	v_pk_mul_f32 v[48:49], v[70:71], v[48:49] op_sel_hi:[0,1]
	v_pk_mul_f32 v[44:45], v[70:71], v[44:45] op_sel_hi:[0,1]
	v_pk_fma_f32 v[40:41], v[136:137], v[42:43], v[40:41]
	v_pk_fma_f32 v[38:39], v[134:135], v[46:47], v[38:39]
	v_pk_fma_f32 v[42:43], v[132:133], v[44:45], v[36:37]
	v_pk_fma_f32 v[44:45], v[130:131], v[48:49], v[34:35]
	v_mul_f32_e32 v34, v39, v39
	v_mul_f32_e32 v35, v41, v41
	v_mul_f32_e32 v36, v45, v45
	v_fmac_f32_e32 v34, v38, v38
	v_fmac_f32_e32 v35, v40, v40
	v_mul_f32_e32 v37, v43, v43
	v_fmac_f32_e32 v36, v44, v44
	v_add_f32_e32 v34, v34, v35
	v_add_f32_e32 v34, v36, v34
	v_fmac_f32_e32 v37, v42, v42
	v_add_f32_e32 v34, v37, v34
	v_add_f32_e32 v34, v51, v34
	ds_bpermute_b32 v35, v116, v34
	v_cvt_pk_bf16_f32 v36, v38, v39
	v_cvt_pk_bf16_f32 v37, v40, v41
	v_lshl_add_u64 v[40:41], s[42:43], 0, v[58:59]
	v_cvt_pk_bf16_f32 v38, v44, v45
	s_waitcnt lgkmcnt(0)
	v_add_f32_e32 v34, v34, v35
	ds_bpermute_b32 v35, v117, v34
	v_cvt_pk_bf16_f32 v39, v42, v43
	s_waitcnt lgkmcnt(0)
	global_store_dwordx4 v218, v[220:223], s[98:99]
	s_nop 0
	v_readfirstlane_b32 s98, v40
	v_readfirstlane_b32 s99, v41
	ds_write_b128 v216, v[36:39]
	ds_read_b128 v[220:223], v217
	s_and_saveexec_b64 s[12:13], s[4:5]
	s_cbranch_execz .LBB0_896
	v_ashrrev_i32_e32 v51, 31, v50
	v_lshl_add_u64 v[36:37], v[50:51], 2, s[46:47]
	s_waitcnt lgkmcnt(0)
	v_add_f32_e32 v34, v34, v35
	global_atomic_add_f32 v[36:37], v34, off
; __host__ __device__ __forceinline__ size_t img_off(int row, int col, int nkt) { return ((size_t)((row >> 7) * nkt + (col >> 6)) << 14) + (size_t)lds_byte(row & 127, col & 63); }
; __device__ __forceinline__ unsigned cvt_pk_bf16(float lo, float hi) { unsigned r; asm volatile("v_cvt_pk_bf16_f32 %0, %1, %2" : "=v"(r) : "v"(lo), "v"(hi)); return r; }
; __device__ __forceinline__ float quad_sum(float s) { s += __shfl_xor(s, 16); s += __shfl_xor(s, 32); return s; }
;     __device__ __forceinline__ void operator()(const f32x4 (&acc)[2][2][4][2], const Unit& u, int wr, int wc, int fr, int fq) const {
;     ...
;         for (int ai = 0; ai < 2; ++ai)
; #pragma unroll
;             for (int m = 0; m < 4; ++m) { const int row = row0 + ai * HALF + m * 16; float s = 0.f; const float rinv = 1.0f / rs[row];
; #pragma unroll
;                 for (int bj = 0; bj < 2; ++bj) { const u32x4 xw = __builtin_nontemporal_load((const u32x4*)(xn + img_off(row, col0 + bj * HALF, 16)));
;                     const f32x4 x0 = (f32x4){__builtin_bit_cast(float, xw.x << 16), __builtin_bit_cast(float, xw.x & 0xffff0000u), __builtin_bit_cast(float, xw.y << 16), __builtin_bit_cast(float, xw.y & 0xffff0000u)} * rinv * gi[bj][0];
;                     const f32x4 x1 = (f32x4){__builtin_bit_cast(float, xw.z << 16), __builtin_bit_cast(float, xw.z & 0xffff0000u), __builtin_bit_cast(float, xw.w << 16), __builtin_bit_cast(float, xw.w & 0xffff0000u)} * rinv * gi[bj][1];
;                     const f32x4 v0 = acc[ai][bj][m][0] + x0, v1 = acc[ai][bj][m][1] + x1;
;                     s += (v0[0] * v0[0] + v0[1] * v0[1]) + (v0[2] * v0[2] + v0[3] * v0[3]) + (v1[0] * v1[0] + v1[1] * v1[1]) + (v1[2] * v1[2] + v1[3] * v1[3]);
;                     u32x4 w; w.x = cvt_pk_bf16(v0[0], v0[1]); w.y = cvt_pk_bf16(v0[2], v0[3]); w.z = cvt_pk_bf16(v1[0], v1[1]); w.w = cvt_pk_bf16(v1[2], v1[3]);
;                     *(u32x4*)((char*)x1b + img_off(row, col0 + bj * HALF, 16)) = w; }
;                 s = quad_sum(s); if (fq == 0) atomicAdd(ss + row, s); }
.LBB0_896:
	s_or_b64 exec, exec, s[12:13]
	s_waitcnt lgkmcnt(0)
	global_load_dword v35, v[154:155], off offset:640
	v_add_u32_e32 v34, 0xa0, v152
	v_lshrrev_b32_e32 v36, 3, v34
	v_and_or_b32 v36, v36, 12, s53
	v_lshlrev_b32_e32 v37, 6, v34
	v_lshlrev_b32_e32 v38, 2, v34
	v_and_or_b32 v37, v37, s73, v165
	v_lshlrev_b32_e32 v36, 10, v36
	v_and_b32_e32 v38, 32, v38
	v_bitop3_b32 v42, v37, v36, v38 bitop3:0xde
	v_or_b32_e32 v40, v68, v42
	v_mov_b32_e32 v41, v69
	v_lshl_add_u64 v[36:37], s[40:41], 0, v[40:41]
	global_load_dwordx4 v[36:39], v[36:37], off nt
	v_mov_b32_e32 v43, v67
	v_or_b32_e32 v42, v66, v42
	v_lshl_add_u64 v[40:41], s[42:43], 0, v[40:41]
	v_lshl_add_u64 v[44:45], s[40:41], 0, v[42:43]
	s_waitcnt vmcnt(1)
	v_div_scale_f32 v50, s[12:13], v35, v35, 1.0
	v_rcp_f32_e32 v51, v50
	v_div_scale_f32 v52, vcc, 1.0, v35, 1.0
	v_fma_f32 v46, -v50, v51, 1.0
	v_fmac_f32_e32 v51, v46, v51
	v_mul_f32_e32 v53, v52, v51
	v_fma_f32 v54, -v50, v53, v52
	v_fmac_f32_e32 v53, v54, v51
	v_fma_f32 v50, -v50, v53, v52
	v_div_fmas_f32 v50, v50, v51, v53
	s_waitcnt vmcnt(0)
	v_lshlrev_b32_e32 v46, 16, v36
	v_and_b32_e32 v47, 0xffff0000, v36
	v_lshlrev_b32_e32 v36, 16, v37
	v_and_b32_e32 v37, 0xffff0000, v37
	v_lshlrev_b32_e32 v48, 16, v38
	v_and_b32_e32 v49, 0xffff0000, v38
	v_lshlrev_b32_e32 v38, 16, v39
	v_and_b32_e32 v39, 0xffff0000, v39
	v_div_fixup_f32 v50, v50, v35, 1.0
	v_pk_mul_f32 v[46:47], v[50:51], v[46:47] op_sel_hi:[0,1]
	v_pk_mul_f32 v[36:37], v[50:51], v[36:37] op_sel_hi:[0,1]
	v_pk_mul_f32 v[48:49], v[50:51], v[48:49] op_sel_hi:[0,1]
	v_pk_mul_f32 v[38:39], v[50:51], v[38:39] op_sel_hi:[0,1]
	v_pk_fma_f32 v[32:33], v[146:147], v[36:37], v[32:33]
	v_pk_fma_f32 v[30:31], v[144:145], v[46:47], v[30:31]
	v_pk_fma_f32 v[36:37], v[150:151], v[38:39], v[28:29]
	v_pk_fma_f32 v[38:39], v[148:149], v[48:49], v[26:27]
	v_cvt_pk_bf16_f32 v26, v30, v31
	v_cvt_pk_bf16_f32 v27, v32, v33
	v_mul_f32_e32 v31, v31, v31
	v_cvt_pk_bf16_f32 v28, v38, v39
	v_cvt_pk_bf16_f32 v29, v36, v37
	s_waitcnt lgkmcnt(0)
	global_store_dwordx4 v218, v[220:223], s[98:99]
	s_nop 0
	v_readfirstlane_b32 s98, v40
	v_readfirstlane_b32 s99, v41
	ds_write_b128 v216, v[26:29]
	ds_read_b128 v[220:223], v217
	global_load_dwordx4 v[26:29], v[44:45], off nt
	v_mul_f32_e32 v33, v33, v33
	v_mul_f32_e32 v35, v39, v39
	v_fmac_f32_e32 v31, v30, v30
	v_fmac_f32_e32 v33, v32, v32
	v_mul_f32_e32 v37, v37, v37
	v_fmac_f32_e32 v35, v38, v38
	v_add_f32_e32 v30, v31, v33
	v_fmac_f32_e32 v37, v36, v36
	v_add_f32_e32 v30, v35, v30
	v_add_f32_e32 v35, v37, v30
	s_waitcnt vmcnt(0)
	v_lshlrev_b32_e32 v30, 16, v26
	v_and_b32_e32 v31, 0xffff0000, v26
	v_lshlrev_b32_e32 v26, 16, v27
	v_and_b32_e32 v27, 0xffff0000, v27
	v_lshlrev_b32_e32 v32, 16, v28
	v_and_b32_e32 v33, 0xffff0000, v28
	v_lshlrev_b32_e32 v28, 16, v29
	v_and_b32_e32 v29, 0xffff0000, v29
	v_pk_mul_f32 v[30:31], v[50:51], v[30:31] op_sel_hi:[0,1]
	v_pk_mul_f32 v[26:27], v[50:51], v[26:27] op_sel_hi:[0,1]
	v_pk_mul_f32 v[32:33], v[50:51], v[32:33] op_sel_hi:[0,1]
	v_pk_mul_f32 v[28:29], v[50:51], v[28:29] op_sel_hi:[0,1]
	v_pk_fma_f32 v[24:25], v[136:137], v[26:27], v[24:25]
	v_pk_fma_f32 v[22:23], v[134:135], v[30:31], v[22:23]
	v_pk_fma_f32 v[26:27], v[132:133], v[28:29], v[20:21]
	v_pk_fma_f32 v[28:29], v[130:131], v[32:33], v[18:19]
	v_mul_f32_e32 v18, v23, v23
	v_mul_f32_e32 v19, v25, v25
	v_mul_f32_e32 v20, v29, v29
	v_fmac_f32_e32 v18, v22, v22
	v_fmac_f32_e32 v19, v24, v24
	v_mul_f32_e32 v21, v27, v27
	v_fmac_f32_e32 v20, v28, v28
	v_add_f32_e32 v18, v18, v19
	v_add_f32_e32 v18, v20, v18
	v_fmac_f32_e32 v21, v26, v26
	v_add_f32_e32 v18, v21, v18
	v_add_f32_e32 v18, v35, v18
	ds_bpermute_b32 v19, v116, v18
	v_cvt_pk_bf16_f32 v20, v22, v23
	v_cvt_pk_bf16_f32 v21, v24, v25
	v_lshl_add_u64 v[24:25], s[42:43], 0, v[42:43]
	v_cvt_pk_bf16_f32 v22, v28, v29
	s_waitcnt lgkmcnt(0)
	v_add_f32_e32 v18, v18, v19
	ds_bpermute_b32 v19, v117, v18
	v_cvt_pk_bf16_f32 v23, v26, v27
	s_waitcnt lgkmcnt(0)
	global_store_dwordx4 v218, v[220:223], s[98:99]
	s_nop 0
	v_readfirstlane_b32 s98, v24
	v_readfirstlane_b32 s99, v25
	ds_write_b128 v216, v[20:23]
	ds_read_b128 v[220:223], v217
	s_and_saveexec_b64 s[12:13], s[4:5]
	s_cbranch_execz .LBB0_898
	v_ashrrev_i32_e32 v35, 31, v34
	v_lshl_add_u64 v[20:21], v[34:35], 2, s[46:47]
	s_waitcnt lgkmcnt(0)
	v_add_f32_e32 v18, v18, v19
	global_atomic_add_f32 v[20:21], v18, off
; __host__ __device__ __forceinline__ size_t img_off(int row, int col, int nkt) { return ((size_t)((row >> 7) * nkt + (col >> 6)) << 14) + (size_t)lds_byte(row & 127, col & 63); }
; __device__ __forceinline__ unsigned cvt_pk_bf16(float lo, float hi) { unsigned r; asm volatile("v_cvt_pk_bf16_f32 %0, %1, %2" : "=v"(r) : "v"(lo), "v"(hi)); return r; }
; __device__ __forceinline__ float quad_sum(float s) { s += __shfl_xor(s, 16); s += __shfl_xor(s, 32); return s; }
;     __device__ __forceinline__ void operator()(const f32x4 (&acc)[2][2][4][2], const Unit& u, int wr, int wc, int fr, int fq) const {
;     ...
;         for (int ai = 0; ai < 2; ++ai)
; #pragma unroll
;             for (int m = 0; m < 4; ++m) { const int row = row0 + ai * HALF + m * 16; float s = 0.f; const float rinv = 1.0f / rs[row];
; #pragma unroll
;                 for (int bj = 0; bj < 2; ++bj) { const u32x4 xw = __builtin_nontemporal_load((const u32x4*)(xn + img_off(row, col0 + bj * HALF, 16)));
;                     const f32x4 x0 = (f32x4){__builtin_bit_cast(float, xw.x << 16), __builtin_bit_cast(float, xw.x & 0xffff0000u), __builtin_bit_cast(float, xw.y << 16), __builtin_bit_cast(float, xw.y & 0xffff0000u)} * rinv * gi[bj][0];
;                     const f32x4 x1 = (f32x4){__builtin_bit_cast(float, xw.z << 16), __builtin_bit_cast(float, xw.z & 0xffff0000u), __builtin_bit_cast(float, xw.w << 16), __builtin_bit_cast(float, xw.w & 0xffff0000u)} * rinv * gi[bj][1];
;                     const f32x4 v0 = acc[ai][bj][m][0] + x0, v1 = acc[ai][bj][m][1] + x1;
;                     s += (v0[0] * v0[0] + v0[1] * v0[1]) + (v0[2] * v0[2] + v0[3] * v0[3]) + (v1[0] * v1[0] + v1[1] * v1[1]) + (v1[2] * v1[2] + v1[3] * v1[3]);
;                     u32x4 w; w.x = cvt_pk_bf16(v0[0], v0[1]); w.y = cvt_pk_bf16(v0[2], v0[3]); w.z = cvt_pk_bf16(v1[0], v1[1]); w.w = cvt_pk_bf16(v1[2], v1[3]);
;                     *(u32x4*)((char*)x1b + img_off(row, col0 + bj * HALF, 16)) = w; }
;                 s = quad_sum(s); if (fq == 0) atomicAdd(ss + row, s); }
.LBB0_898:
	s_or_b64 exec, exec, s[12:13]
	s_waitcnt lgkmcnt(0)
	global_load_dword v19, v[154:155], off offset:704
	v_add_u32_e32 v18, 0xb0, v152
	v_lshrrev_b32_e32 v20, 3, v18
	v_and_or_b32 v20, v20, 14, s53
	v_lshlrev_b32_e32 v21, 6, v18
	v_lshlrev_b32_e32 v22, 2, v18
	v_and_or_b32 v21, v21, s73, v165
	v_lshlrev_b32_e32 v20, 10, v20
	v_and_b32_e32 v22, 32, v22
	v_bitop3_b32 v24, v21, v20, v22 bitop3:0xde
	v_or_b32_e32 v68, v68, v24
	v_lshl_add_u64 v[20:21], s[40:41], 0, v[68:69]
	global_load_dwordx4 v[20:23], v[20:21], off nt
	v_or_b32_e32 v66, v66, v24
	v_lshl_add_u64 v[24:25], s[42:43], 0, v[68:69]
	v_lshl_add_u64 v[26:27], s[40:41], 0, v[66:67]
	s_waitcnt vmcnt(1)
	v_div_scale_f32 v32, s[12:13], v19, v19, 1.0
	v_rcp_f32_e32 v33, v32
	v_div_scale_f32 v34, vcc, 1.0, v19, 1.0
	v_fma_f32 v28, -v32, v33, 1.0
	v_fmac_f32_e32 v33, v28, v33
	v_mul_f32_e32 v35, v34, v33
	v_fma_f32 v36, -v32, v35, v34
	v_fmac_f32_e32 v35, v36, v33
	v_fma_f32 v32, -v32, v35, v34
	v_div_fmas_f32 v32, v32, v33, v35
	s_waitcnt vmcnt(0)
	v_lshlrev_b32_e32 v28, 16, v20
	v_and_b32_e32 v29, 0xffff0000, v20
	v_lshlrev_b32_e32 v20, 16, v21
	v_and_b32_e32 v21, 0xffff0000, v21
	v_lshlrev_b32_e32 v30, 16, v22
	v_and_b32_e32 v31, 0xffff0000, v22
	v_lshlrev_b32_e32 v22, 16, v23
	v_and_b32_e32 v23, 0xffff0000, v23
	v_div_fixup_f32 v32, v32, v19, 1.0
	v_pk_mul_f32 v[28:29], v[32:33], v[28:29] op_sel_hi:[0,1]
	v_pk_mul_f32 v[20:21], v[32:33], v[20:21] op_sel_hi:[0,1]
	v_pk_mul_f32 v[30:31], v[32:33], v[30:31] op_sel_hi:[0,1]
	v_pk_mul_f32 v[22:23], v[32:33], v[22:23] op_sel_hi:[0,1]
	v_pk_fma_f32 v[16:17], v[146:147], v[20:21], v[16:17]
	v_pk_fma_f32 v[14:15], v[144:145], v[28:29], v[14:15]
	v_pk_fma_f32 v[20:21], v[150:151], v[22:23], v[12:13]
	v_pk_fma_f32 v[22:23], v[148:149], v[30:31], v[10:11]
	v_cvt_pk_bf16_f32 v10, v14, v15
	v_cvt_pk_bf16_f32 v11, v16, v17
	v_mul_f32_e32 v15, v15, v15
	v_cvt_pk_bf16_f32 v12, v22, v23
	v_cvt_pk_bf16_f32 v13, v20, v21
	s_waitcnt lgkmcnt(0)
	global_store_dwordx4 v218, v[220:223], s[98:99]
	s_nop 0
	v_readfirstlane_b32 s98, v24
	v_readfirstlane_b32 s99, v25
	ds_write_b128 v216, v[10:13]
	ds_read_b128 v[220:223], v217
	global_load_dwordx4 v[10:13], v[26:27], off nt
	v_mul_f32_e32 v17, v17, v17
	v_mul_f32_e32 v19, v23, v23
	v_fmac_f32_e32 v15, v14, v14
	v_fmac_f32_e32 v17, v16, v16
	v_mul_f32_e32 v21, v21, v21
	v_fmac_f32_e32 v19, v22, v22
	v_add_f32_e32 v14, v15, v17
	v_fmac_f32_e32 v21, v20, v20
	v_add_f32_e32 v14, v19, v14
	v_add_f32_e32 v19, v21, v14
	s_waitcnt vmcnt(0)
	v_lshlrev_b32_e32 v14, 16, v10
	v_and_b32_e32 v15, 0xffff0000, v10
	v_lshlrev_b32_e32 v10, 16, v11
	v_and_b32_e32 v11, 0xffff0000, v11
	v_lshlrev_b32_e32 v16, 16, v12
	v_and_b32_e32 v17, 0xffff0000, v12
	v_lshlrev_b32_e32 v12, 16, v13
	v_and_b32_e32 v13, 0xffff0000, v13
	v_pk_mul_f32 v[14:15], v[32:33], v[14:15] op_sel_hi:[0,1]
	v_pk_mul_f32 v[10:11], v[32:33], v[10:11] op_sel_hi:[0,1]
	v_pk_mul_f32 v[16:17], v[32:33], v[16:17] op_sel_hi:[0,1]
	v_pk_mul_f32 v[12:13], v[32:33], v[12:13] op_sel_hi:[0,1]
	v_pk_fma_f32 v[8:9], v[136:137], v[10:11], v[8:9]
	v_pk_fma_f32 v[6:7], v[134:135], v[14:15], v[6:7]
	v_pk_fma_f32 v[10:11], v[132:133], v[12:13], v[4:5]
	v_pk_fma_f32 v[12:13], v[130:131], v[16:17], v[2:3]
	v_mul_f32_e32 v2, v7, v7
	v_mul_f32_e32 v3, v9, v9
	v_mul_f32_e32 v4, v13, v13
	v_fmac_f32_e32 v2, v6, v6
	v_fmac_f32_e32 v3, v8, v8
	v_mul_f32_e32 v5, v11, v11
	v_fmac_f32_e32 v4, v12, v12
	v_add_f32_e32 v2, v2, v3
	v_add_f32_e32 v2, v4, v2
	v_fmac_f32_e32 v5, v10, v10
	v_add_f32_e32 v2, v5, v2
	v_add_f32_e32 v2, v19, v2
	ds_bpermute_b32 v3, v116, v2
	v_cvt_pk_bf16_f32 v4, v6, v7
	v_cvt_pk_bf16_f32 v5, v8, v9
	v_lshl_add_u64 v[8:9], s[42:43], 0, v[66:67]
	v_cvt_pk_bf16_f32 v6, v12, v13
	s_waitcnt lgkmcnt(0)
	v_add_f32_e32 v2, v2, v3
	ds_bpermute_b32 v3, v117, v2
	v_cvt_pk_bf16_f32 v7, v10, v11
	s_waitcnt lgkmcnt(0)
	global_store_dwordx4 v218, v[220:223], s[98:99]
	s_nop 0
	v_readfirstlane_b32 s98, v8
	v_readfirstlane_b32 s99, v9
	ds_write_b128 v216, v[4:7]
	ds_read_b128 v[220:223], v217
	s_nop 1
	s_waitcnt lgkmcnt(0)
	global_store_dwordx4 v218, v[220:223], s[98:99]
	s_and_saveexec_b64 s[12:13], s[4:5]
	s_cbranch_execz .LBB0_900
	v_ashrrev_i32_e32 v19, 31, v18
	v_lshl_add_u64 v[4:5], v[18:19], 2, s[46:47]
	s_waitcnt lgkmcnt(0)
	v_add_f32_e32 v2, v2, v3
	global_atomic_add_f32 v[4:5], v2, off
